# P0 adaLN: the 34 silu(cond) input loads of a thread issued as one batch instead of load->wait per element
# speedup vs baseline: 1.0096x; 1.0096x over previous
.LBB0_17:
	s_load_dwordx16 s[60:75], s[0:1], 0x0
	s_cmp_lt_i32 s80, 1
	s_cselect_b64 s[0:1], -1, 0
	s_cmp_gt_i32 s81, 0
	v_writelane_b32 v254, s2, 4
	s_cselect_b64 s[2:3], -1, 0
	s_and_b64 s[2:3], s[0:1], s[2:3]
	s_andn2_b64 vcc, exec, s[2:3]
	s_cbranch_vccnz .LBB0_81
	v_readlane_b32 s0, v254, 4
	s_cmp_gt_u32 s0, 47
	s_cbranch_scc1 .LBB0_36
	v_mov_b32_e32 v3, 0
	v_lshlrev_b32_e32 v0, 2, v193
	v_mov_b32_e32 v1, v3
	v_add_u32_e32 v6, 0, v0
	s_waitcnt lgkmcnt(0)
	v_lshl_add_u64 v[4:5], s[62:63], 0, v[0:1]
	v_lshl_add_u64 v[10:11], s[66:67], 0, v[0:1]
	s_mov_b64 s[6:7], 0x1000
	global_load_dword v16, v[4:5], off
	global_load_dword v17, v[4:5], off offset:2048
	v_lshl_add_u64 v[8:9], v[4:5], 0, s[6:7]
	global_load_dword v18, v[8:9], off
	global_load_dword v19, v[8:9], off offset:2048
	v_lshl_add_u64 v[4:5], v[8:9], 0, s[6:7]
	global_load_dword v20, v[4:5], off
	global_load_dword v21, v[4:5], off offset:2048
	v_lshl_add_u64 v[8:9], v[4:5], 0, s[6:7]
	global_load_dword v22, v[8:9], off
	global_load_dword v23, v[8:9], off offset:2048
	v_lshl_add_u64 v[4:5], v[8:9], 0, s[6:7]
	global_load_dword v24, v[4:5], off
	global_load_dword v25, v[4:5], off offset:2048
	v_lshl_add_u64 v[8:9], v[4:5], 0, s[6:7]
	global_load_dword v26, v[8:9], off
	global_load_dword v27, v[8:9], off offset:2048
	v_lshl_add_u64 v[4:5], v[8:9], 0, s[6:7]
	global_load_dword v28, v[4:5], off
	global_load_dword v29, v[4:5], off offset:2048
	v_lshl_add_u64 v[8:9], v[4:5], 0, s[6:7]
	global_load_dword v30, v[8:9], off
	global_load_dword v31, v[8:9], off offset:2048
	v_lshl_add_u64 v[4:5], v[8:9], 0, s[6:7]
	global_load_dword v32, v[4:5], off
	global_load_dword v33, v[4:5], off offset:2048
	v_lshl_add_u64 v[8:9], v[4:5], 0, s[6:7]
	global_load_dword v34, v[8:9], off
	global_load_dword v35, v[8:9], off offset:2048
	v_lshl_add_u64 v[4:5], v[8:9], 0, s[6:7]
	global_load_dword v36, v[4:5], off
	global_load_dword v37, v[4:5], off offset:2048
	v_lshl_add_u64 v[8:9], v[4:5], 0, s[6:7]
	global_load_dword v38, v[8:9], off
	global_load_dword v39, v[8:9], off offset:2048
	v_lshl_add_u64 v[4:5], v[8:9], 0, s[6:7]
	global_load_dword v40, v[4:5], off
	global_load_dword v41, v[4:5], off offset:2048
	v_lshl_add_u64 v[8:9], v[4:5], 0, s[6:7]
	global_load_dword v42, v[8:9], off
	global_load_dword v43, v[8:9], off offset:2048
	v_lshl_add_u64 v[4:5], v[8:9], 0, s[6:7]
	global_load_dword v44, v[4:5], off
	global_load_dword v45, v[4:5], off offset:2048
	v_lshl_add_u64 v[8:9], v[4:5], 0, s[6:7]
	global_load_dword v46, v[8:9], off
	global_load_dword v47, v[8:9], off offset:2048
	global_load_dword v48, v[10:11], off
	global_load_dword v49, v[10:11], off offset:2048
	s_waitcnt vmcnt(33)
	v_mul_f32_e32 v7, 0xbfb8aa3b, v16
	v_exp_f32_e32 v7, v7
	s_nop 0
	v_add_f32_e32 v7, 1.0, v7
	v_div_scale_f32 v8, s[10:11], v7, v7, v16
	v_rcp_f32_e32 v9, v8
	v_div_scale_f32 v10, vcc, v16, v7, v16
	v_fma_f32 v11, -v8, v9, 1.0
	v_fmac_f32_e32 v9, v11, v9
	v_mul_f32_e32 v11, v10, v9
	v_fma_f32 v12, -v8, v11, v10
	v_fmac_f32_e32 v11, v12, v9
	v_fma_f32 v8, -v8, v11, v10
	v_div_fmas_f32 v8, v8, v9, v11
	v_div_fixup_f32 v2, v8, v7, v16
	ds_write_b32 v6, v2 offset:0
	s_waitcnt vmcnt(32)
	v_mul_f32_e32 v7, 0xbfb8aa3b, v17
	v_exp_f32_e32 v7, v7
	s_nop 0
	v_add_f32_e32 v7, 1.0, v7
	v_div_scale_f32 v8, s[10:11], v7, v7, v17
	v_rcp_f32_e32 v9, v8
	v_div_scale_f32 v10, vcc, v17, v7, v17
	v_fma_f32 v11, -v8, v9, 1.0
	v_fmac_f32_e32 v9, v11, v9
	v_mul_f32_e32 v11, v10, v9
	v_fma_f32 v12, -v8, v11, v10
	v_fmac_f32_e32 v11, v12, v9
	v_fma_f32 v8, -v8, v11, v10
	v_div_fmas_f32 v8, v8, v9, v11
	v_div_fixup_f32 v2, v8, v7, v17
	ds_write_b32 v6, v2 offset:2048
	s_waitcnt vmcnt(31)
	v_mul_f32_e32 v7, 0xbfb8aa3b, v18
	v_exp_f32_e32 v7, v7
	s_nop 0
	v_add_f32_e32 v7, 1.0, v7
	v_div_scale_f32 v8, s[10:11], v7, v7, v18
	v_rcp_f32_e32 v9, v8
	v_div_scale_f32 v10, vcc, v18, v7, v18
	v_fma_f32 v11, -v8, v9, 1.0
	v_fmac_f32_e32 v9, v11, v9
	v_mul_f32_e32 v11, v10, v9
	v_fma_f32 v12, -v8, v11, v10
	v_fmac_f32_e32 v11, v12, v9
	v_fma_f32 v8, -v8, v11, v10
	v_div_fmas_f32 v8, v8, v9, v11
	v_div_fixup_f32 v2, v8, v7, v18
	ds_write_b32 v6, v2 offset:4096
	s_waitcnt vmcnt(30)
	v_mul_f32_e32 v7, 0xbfb8aa3b, v19
	v_exp_f32_e32 v7, v7
	s_nop 0
	v_add_f32_e32 v7, 1.0, v7
	v_div_scale_f32 v8, s[10:11], v7, v7, v19
	v_rcp_f32_e32 v9, v8
	v_div_scale_f32 v10, vcc, v19, v7, v19
	v_fma_f32 v11, -v8, v9, 1.0
	v_fmac_f32_e32 v9, v11, v9
	v_mul_f32_e32 v11, v10, v9
	v_fma_f32 v12, -v8, v11, v10
	v_fmac_f32_e32 v11, v12, v9
	v_fma_f32 v8, -v8, v11, v10
	v_div_fmas_f32 v8, v8, v9, v11
	v_div_fixup_f32 v2, v8, v7, v19
	ds_write_b32 v6, v2 offset:6144
	s_waitcnt vmcnt(29)
	v_mul_f32_e32 v7, 0xbfb8aa3b, v20
	v_exp_f32_e32 v7, v7
	s_nop 0
	v_add_f32_e32 v7, 1.0, v7
	v_div_scale_f32 v8, s[10:11], v7, v7, v20
	v_rcp_f32_e32 v9, v8
	v_div_scale_f32 v10, vcc, v20, v7, v20
	v_fma_f32 v11, -v8, v9, 1.0
	v_fmac_f32_e32 v9, v11, v9
	v_mul_f32_e32 v11, v10, v9
	v_fma_f32 v12, -v8, v11, v10
	v_fmac_f32_e32 v11, v12, v9
	v_fma_f32 v8, -v8, v11, v10
	v_div_fmas_f32 v8, v8, v9, v11
	v_div_fixup_f32 v2, v8, v7, v20
	ds_write_b32 v6, v2 offset:8192
	s_waitcnt vmcnt(28)
	v_mul_f32_e32 v7, 0xbfb8aa3b, v21
	v_exp_f32_e32 v7, v7
	s_nop 0
	v_add_f32_e32 v7, 1.0, v7
	v_div_scale_f32 v8, s[10:11], v7, v7, v21
	v_rcp_f32_e32 v9, v8
	v_div_scale_f32 v10, vcc, v21, v7, v21
	v_fma_f32 v11, -v8, v9, 1.0
	v_fmac_f32_e32 v9, v11, v9
	v_mul_f32_e32 v11, v10, v9
	v_fma_f32 v12, -v8, v11, v10
	v_fmac_f32_e32 v11, v12, v9
	v_fma_f32 v8, -v8, v11, v10
	v_div_fmas_f32 v8, v8, v9, v11
	v_div_fixup_f32 v2, v8, v7, v21
	ds_write_b32 v6, v2 offset:10240
	s_waitcnt vmcnt(27)
	v_mul_f32_e32 v7, 0xbfb8aa3b, v22
	v_exp_f32_e32 v7, v7
	s_nop 0
	v_add_f32_e32 v7, 1.0, v7
	v_div_scale_f32 v8, s[10:11], v7, v7, v22
	v_rcp_f32_e32 v9, v8
	v_div_scale_f32 v10, vcc, v22, v7, v22
	v_fma_f32 v11, -v8, v9, 1.0
	v_fmac_f32_e32 v9, v11, v9
	v_mul_f32_e32 v11, v10, v9
	v_fma_f32 v12, -v8, v11, v10
	v_fmac_f32_e32 v11, v12, v9
	v_fma_f32 v8, -v8, v11, v10
	v_div_fmas_f32 v8, v8, v9, v11
	v_div_fixup_f32 v2, v8, v7, v22
	ds_write_b32 v6, v2 offset:12288
	s_waitcnt vmcnt(26)
	v_mul_f32_e32 v7, 0xbfb8aa3b, v23
	v_exp_f32_e32 v7, v7
	s_nop 0
	v_add_f32_e32 v7, 1.0, v7
	v_div_scale_f32 v8, s[10:11], v7, v7, v23
	v_rcp_f32_e32 v9, v8
	v_div_scale_f32 v10, vcc, v23, v7, v23
	v_fma_f32 v11, -v8, v9, 1.0
	v_fmac_f32_e32 v9, v11, v9
	v_mul_f32_e32 v11, v10, v9
	v_fma_f32 v12, -v8, v11, v10
	v_fmac_f32_e32 v11, v12, v9
	v_fma_f32 v8, -v8, v11, v10
	v_div_fmas_f32 v8, v8, v9, v11
	v_div_fixup_f32 v2, v8, v7, v23
	ds_write_b32 v6, v2 offset:14336
	s_waitcnt vmcnt(25)
	v_mul_f32_e32 v7, 0xbfb8aa3b, v24
	v_exp_f32_e32 v7, v7
	s_nop 0
	v_add_f32_e32 v7, 1.0, v7
	v_div_scale_f32 v8, s[10:11], v7, v7, v24
	v_rcp_f32_e32 v9, v8
	v_div_scale_f32 v10, vcc, v24, v7, v24
	v_fma_f32 v11, -v8, v9, 1.0
	v_fmac_f32_e32 v9, v11, v9
	v_mul_f32_e32 v11, v10, v9
	v_fma_f32 v12, -v8, v11, v10
	v_fmac_f32_e32 v11, v12, v9
	v_fma_f32 v8, -v8, v11, v10
	v_div_fmas_f32 v8, v8, v9, v11
	v_div_fixup_f32 v2, v8, v7, v24
	ds_write_b32 v6, v2 offset:16384
	s_waitcnt vmcnt(24)
	v_mul_f32_e32 v7, 0xbfb8aa3b, v25
	v_exp_f32_e32 v7, v7
	s_nop 0
	v_add_f32_e32 v7, 1.0, v7
	v_div_scale_f32 v8, s[10:11], v7, v7, v25
	v_rcp_f32_e32 v9, v8
	v_div_scale_f32 v10, vcc, v25, v7, v25
	v_fma_f32 v11, -v8, v9, 1.0
	v_fmac_f32_e32 v9, v11, v9
	v_mul_f32_e32 v11, v10, v9
	v_fma_f32 v12, -v8, v11, v10
	v_fmac_f32_e32 v11, v12, v9
	v_fma_f32 v8, -v8, v11, v10
	v_div_fmas_f32 v8, v8, v9, v11
	v_div_fixup_f32 v2, v8, v7, v25
	ds_write_b32 v6, v2 offset:18432
	s_waitcnt vmcnt(23)
	v_mul_f32_e32 v7, 0xbfb8aa3b, v26
	v_exp_f32_e32 v7, v7
	s_nop 0
	v_add_f32_e32 v7, 1.0, v7
	v_div_scale_f32 v8, s[10:11], v7, v7, v26
	v_rcp_f32_e32 v9, v8
	v_div_scale_f32 v10, vcc, v26, v7, v26
	v_fma_f32 v11, -v8, v9, 1.0
	v_fmac_f32_e32 v9, v11, v9
	v_mul_f32_e32 v11, v10, v9
	v_fma_f32 v12, -v8, v11, v10
	v_fmac_f32_e32 v11, v12, v9
	v_fma_f32 v8, -v8, v11, v10
	v_div_fmas_f32 v8, v8, v9, v11
	v_div_fixup_f32 v2, v8, v7, v26
	ds_write_b32 v6, v2 offset:20480
	s_waitcnt vmcnt(22)
	v_mul_f32_e32 v7, 0xbfb8aa3b, v27
	v_exp_f32_e32 v7, v7
	s_nop 0
	v_add_f32_e32 v7, 1.0, v7
	v_div_scale_f32 v8, s[10:11], v7, v7, v27
	v_rcp_f32_e32 v9, v8
	v_div_scale_f32 v10, vcc, v27, v7, v27
	v_fma_f32 v11, -v8, v9, 1.0
	v_fmac_f32_e32 v9, v11, v9
	v_mul_f32_e32 v11, v10, v9
	v_fma_f32 v12, -v8, v11, v10
	v_fmac_f32_e32 v11, v12, v9
	v_fma_f32 v8, -v8, v11, v10
	v_div_fmas_f32 v8, v8, v9, v11
	v_div_fixup_f32 v2, v8, v7, v27
	ds_write_b32 v6, v2 offset:22528
	s_waitcnt vmcnt(21)
	v_mul_f32_e32 v7, 0xbfb8aa3b, v28
	v_exp_f32_e32 v7, v7
	s_nop 0
	v_add_f32_e32 v7, 1.0, v7
	v_div_scale_f32 v8, s[10:11], v7, v7, v28
	v_rcp_f32_e32 v9, v8
	v_div_scale_f32 v10, vcc, v28, v7, v28
	v_fma_f32 v11, -v8, v9, 1.0
	v_fmac_f32_e32 v9, v11, v9
	v_mul_f32_e32 v11, v10, v9
	v_fma_f32 v12, -v8, v11, v10
	v_fmac_f32_e32 v11, v12, v9
	v_fma_f32 v8, -v8, v11, v10
	v_div_fmas_f32 v8, v8, v9, v11
	v_div_fixup_f32 v2, v8, v7, v28
	ds_write_b32 v6, v2 offset:24576
	s_waitcnt vmcnt(20)
	v_mul_f32_e32 v7, 0xbfb8aa3b, v29
	v_exp_f32_e32 v7, v7
	s_nop 0
	v_add_f32_e32 v7, 1.0, v7
	v_div_scale_f32 v8, s[10:11], v7, v7, v29
	v_rcp_f32_e32 v9, v8
	v_div_scale_f32 v10, vcc, v29, v7, v29
	v_fma_f32 v11, -v8, v9, 1.0
	v_fmac_f32_e32 v9, v11, v9
	v_mul_f32_e32 v11, v10, v9
	v_fma_f32 v12, -v8, v11, v10
	v_fmac_f32_e32 v11, v12, v9
	v_fma_f32 v8, -v8, v11, v10
	v_div_fmas_f32 v8, v8, v9, v11
	v_div_fixup_f32 v2, v8, v7, v29
	ds_write_b32 v6, v2 offset:26624
	s_waitcnt vmcnt(19)
	v_mul_f32_e32 v7, 0xbfb8aa3b, v30
	v_exp_f32_e32 v7, v7
	s_nop 0
	v_add_f32_e32 v7, 1.0, v7
	v_div_scale_f32 v8, s[10:11], v7, v7, v30
	v_rcp_f32_e32 v9, v8
	v_div_scale_f32 v10, vcc, v30, v7, v30
	v_fma_f32 v11, -v8, v9, 1.0
	v_fmac_f32_e32 v9, v11, v9
	v_mul_f32_e32 v11, v10, v9
	v_fma_f32 v12, -v8, v11, v10
	v_fmac_f32_e32 v11, v12, v9
	v_fma_f32 v8, -v8, v11, v10
	v_div_fmas_f32 v8, v8, v9, v11
	v_div_fixup_f32 v2, v8, v7, v30
	ds_write_b32 v6, v2 offset:28672
	s_waitcnt vmcnt(18)
	v_mul_f32_e32 v7, 0xbfb8aa3b, v31
	v_exp_f32_e32 v7, v7
	s_nop 0
	v_add_f32_e32 v7, 1.0, v7
	v_div_scale_f32 v8, s[10:11], v7, v7, v31
	v_rcp_f32_e32 v9, v8
	v_div_scale_f32 v10, vcc, v31, v7, v31
	v_fma_f32 v11, -v8, v9, 1.0
	v_fmac_f32_e32 v9, v11, v9
	v_mul_f32_e32 v11, v10, v9
	v_fma_f32 v12, -v8, v11, v10
	v_fmac_f32_e32 v11, v12, v9
	v_fma_f32 v8, -v8, v11, v10
	v_div_fmas_f32 v8, v8, v9, v11
	v_div_fixup_f32 v2, v8, v7, v31
	ds_write_b32 v6, v2 offset:30720
	s_waitcnt vmcnt(17)
	v_mul_f32_e32 v7, 0xbfb8aa3b, v32
	v_exp_f32_e32 v7, v7
	s_nop 0
	v_add_f32_e32 v7, 1.0, v7
	v_div_scale_f32 v8, s[10:11], v7, v7, v32
	v_rcp_f32_e32 v9, v8
	v_div_scale_f32 v10, vcc, v32, v7, v32
	v_fma_f32 v11, -v8, v9, 1.0
	v_fmac_f32_e32 v9, v11, v9
	v_mul_f32_e32 v11, v10, v9
	v_fma_f32 v12, -v8, v11, v10
	v_fmac_f32_e32 v11, v12, v9
	v_fma_f32 v8, -v8, v11, v10
	v_div_fmas_f32 v8, v8, v9, v11
	v_div_fixup_f32 v2, v8, v7, v32
	ds_write_b32 v6, v2 offset:32768
	s_waitcnt vmcnt(16)
	v_mul_f32_e32 v7, 0xbfb8aa3b, v33
	v_exp_f32_e32 v7, v7
	s_nop 0
	v_add_f32_e32 v7, 1.0, v7
	v_div_scale_f32 v8, s[10:11], v7, v7, v33
	v_rcp_f32_e32 v9, v8
	v_div_scale_f32 v10, vcc, v33, v7, v33
	v_fma_f32 v11, -v8, v9, 1.0
	v_fmac_f32_e32 v9, v11, v9
	v_mul_f32_e32 v11, v10, v9
	v_fma_f32 v12, -v8, v11, v10
	v_fmac_f32_e32 v11, v12, v9
	v_fma_f32 v8, -v8, v11, v10
	v_div_fmas_f32 v8, v8, v9, v11
	v_div_fixup_f32 v2, v8, v7, v33
	ds_write_b32 v6, v2 offset:34816
	s_waitcnt vmcnt(15)
	v_mul_f32_e32 v7, 0xbfb8aa3b, v34
	v_exp_f32_e32 v7, v7
	s_nop 0
	v_add_f32_e32 v7, 1.0, v7
	v_div_scale_f32 v8, s[10:11], v7, v7, v34
	v_rcp_f32_e32 v9, v8
	v_div_scale_f32 v10, vcc, v34, v7, v34
	v_fma_f32 v11, -v8, v9, 1.0
	v_fmac_f32_e32 v9, v11, v9
	v_mul_f32_e32 v11, v10, v9
	v_fma_f32 v12, -v8, v11, v10
	v_fmac_f32_e32 v11, v12, v9
	v_fma_f32 v8, -v8, v11, v10
	v_div_fmas_f32 v8, v8, v9, v11
	v_div_fixup_f32 v2, v8, v7, v34
	ds_write_b32 v6, v2 offset:36864
	s_waitcnt vmcnt(14)
	v_mul_f32_e32 v7, 0xbfb8aa3b, v35
	v_exp_f32_e32 v7, v7
	s_nop 0
	v_add_f32_e32 v7, 1.0, v7
	v_div_scale_f32 v8, s[10:11], v7, v7, v35
	v_rcp_f32_e32 v9, v8
	v_div_scale_f32 v10, vcc, v35, v7, v35
	v_fma_f32 v11, -v8, v9, 1.0
	v_fmac_f32_e32 v9, v11, v9
	v_mul_f32_e32 v11, v10, v9
	v_fma_f32 v12, -v8, v11, v10
	v_fmac_f32_e32 v11, v12, v9
	v_fma_f32 v8, -v8, v11, v10
	v_div_fmas_f32 v8, v8, v9, v11
	v_div_fixup_f32 v2, v8, v7, v35
	ds_write_b32 v6, v2 offset:38912
	s_waitcnt vmcnt(13)
	v_mul_f32_e32 v7, 0xbfb8aa3b, v36
	v_exp_f32_e32 v7, v7
	s_nop 0
	v_add_f32_e32 v7, 1.0, v7
	v_div_scale_f32 v8, s[10:11], v7, v7, v36
	v_rcp_f32_e32 v9, v8
	v_div_scale_f32 v10, vcc, v36, v7, v36
	v_fma_f32 v11, -v8, v9, 1.0
	v_fmac_f32_e32 v9, v11, v9
	v_mul_f32_e32 v11, v10, v9
	v_fma_f32 v12, -v8, v11, v10
	v_fmac_f32_e32 v11, v12, v9
	v_fma_f32 v8, -v8, v11, v10
	v_div_fmas_f32 v8, v8, v9, v11
	v_div_fixup_f32 v2, v8, v7, v36
	ds_write_b32 v6, v2 offset:40960
	s_waitcnt vmcnt(12)
	v_mul_f32_e32 v7, 0xbfb8aa3b, v37
	v_exp_f32_e32 v7, v7
	s_nop 0
	v_add_f32_e32 v7, 1.0, v7
	v_div_scale_f32 v8, s[10:11], v7, v7, v37
	v_rcp_f32_e32 v9, v8
	v_div_scale_f32 v10, vcc, v37, v7, v37
	v_fma_f32 v11, -v8, v9, 1.0
	v_fmac_f32_e32 v9, v11, v9
	v_mul_f32_e32 v11, v10, v9
	v_fma_f32 v12, -v8, v11, v10
	v_fmac_f32_e32 v11, v12, v9
	v_fma_f32 v8, -v8, v11, v10
	v_div_fmas_f32 v8, v8, v9, v11
	v_div_fixup_f32 v2, v8, v7, v37
	ds_write_b32 v6, v2 offset:43008
	s_waitcnt vmcnt(11)
	v_mul_f32_e32 v7, 0xbfb8aa3b, v38
	v_exp_f32_e32 v7, v7
	s_nop 0
	v_add_f32_e32 v7, 1.0, v7
	v_div_scale_f32 v8, s[10:11], v7, v7, v38
	v_rcp_f32_e32 v9, v8
	v_div_scale_f32 v10, vcc, v38, v7, v38
	v_fma_f32 v11, -v8, v9, 1.0
	v_fmac_f32_e32 v9, v11, v9
	v_mul_f32_e32 v11, v10, v9
	v_fma_f32 v12, -v8, v11, v10
	v_fmac_f32_e32 v11, v12, v9
	v_fma_f32 v8, -v8, v11, v10
	v_div_fmas_f32 v8, v8, v9, v11
	v_div_fixup_f32 v2, v8, v7, v38
	ds_write_b32 v6, v2 offset:45056
	s_waitcnt vmcnt(10)
	v_mul_f32_e32 v7, 0xbfb8aa3b, v39
	v_exp_f32_e32 v7, v7
	s_nop 0
	v_add_f32_e32 v7, 1.0, v7
	v_div_scale_f32 v8, s[10:11], v7, v7, v39
	v_rcp_f32_e32 v9, v8
	v_div_scale_f32 v10, vcc, v39, v7, v39
	v_fma_f32 v11, -v8, v9, 1.0
	v_fmac_f32_e32 v9, v11, v9
	v_mul_f32_e32 v11, v10, v9
	v_fma_f32 v12, -v8, v11, v10
	v_fmac_f32_e32 v11, v12, v9
	v_fma_f32 v8, -v8, v11, v10
	v_div_fmas_f32 v8, v8, v9, v11
	v_div_fixup_f32 v2, v8, v7, v39
	ds_write_b32 v6, v2 offset:47104
	s_waitcnt vmcnt(9)
	v_mul_f32_e32 v7, 0xbfb8aa3b, v40
	v_exp_f32_e32 v7, v7
	s_nop 0
	v_add_f32_e32 v7, 1.0, v7
	v_div_scale_f32 v8, s[10:11], v7, v7, v40
	v_rcp_f32_e32 v9, v8
	v_div_scale_f32 v10, vcc, v40, v7, v40
	v_fma_f32 v11, -v8, v9, 1.0
	v_fmac_f32_e32 v9, v11, v9
	v_mul_f32_e32 v11, v10, v9
	v_fma_f32 v12, -v8, v11, v10
	v_fmac_f32_e32 v11, v12, v9
	v_fma_f32 v8, -v8, v11, v10
	v_div_fmas_f32 v8, v8, v9, v11
	v_div_fixup_f32 v2, v8, v7, v40
	ds_write_b32 v6, v2 offset:49152
	s_waitcnt vmcnt(8)
	v_mul_f32_e32 v7, 0xbfb8aa3b, v41
	v_exp_f32_e32 v7, v7
	s_nop 0
	v_add_f32_e32 v7, 1.0, v7
	v_div_scale_f32 v8, s[10:11], v7, v7, v41
	v_rcp_f32_e32 v9, v8
	v_div_scale_f32 v10, vcc, v41, v7, v41
	v_fma_f32 v11, -v8, v9, 1.0
	v_fmac_f32_e32 v9, v11, v9
	v_mul_f32_e32 v11, v10, v9
	v_fma_f32 v12, -v8, v11, v10
	v_fmac_f32_e32 v11, v12, v9
	v_fma_f32 v8, -v8, v11, v10
	v_div_fmas_f32 v8, v8, v9, v11
	v_div_fixup_f32 v2, v8, v7, v41
	ds_write_b32 v6, v2 offset:51200
	s_waitcnt vmcnt(7)
	v_mul_f32_e32 v7, 0xbfb8aa3b, v42
	v_exp_f32_e32 v7, v7
	s_nop 0
	v_add_f32_e32 v7, 1.0, v7
	v_div_scale_f32 v8, s[10:11], v7, v7, v42
	v_rcp_f32_e32 v9, v8
	v_div_scale_f32 v10, vcc, v42, v7, v42
	v_fma_f32 v11, -v8, v9, 1.0
	v_fmac_f32_e32 v9, v11, v9
	v_mul_f32_e32 v11, v10, v9
	v_fma_f32 v12, -v8, v11, v10
	v_fmac_f32_e32 v11, v12, v9
	v_fma_f32 v8, -v8, v11, v10
	v_div_fmas_f32 v8, v8, v9, v11
	v_div_fixup_f32 v2, v8, v7, v42
	ds_write_b32 v6, v2 offset:53248
	s_waitcnt vmcnt(6)
	v_mul_f32_e32 v7, 0xbfb8aa3b, v43
	v_exp_f32_e32 v7, v7
	s_nop 0
	v_add_f32_e32 v7, 1.0, v7
	v_div_scale_f32 v8, s[10:11], v7, v7, v43
	v_rcp_f32_e32 v9, v8
	v_div_scale_f32 v10, vcc, v43, v7, v43
	v_fma_f32 v11, -v8, v9, 1.0
	v_fmac_f32_e32 v9, v11, v9
	v_mul_f32_e32 v11, v10, v9
	v_fma_f32 v12, -v8, v11, v10
	v_fmac_f32_e32 v11, v12, v9
	v_fma_f32 v8, -v8, v11, v10
	v_div_fmas_f32 v8, v8, v9, v11
	v_div_fixup_f32 v2, v8, v7, v43
	ds_write_b32 v6, v2 offset:55296
	s_waitcnt vmcnt(5)
	v_mul_f32_e32 v7, 0xbfb8aa3b, v44
	v_exp_f32_e32 v7, v7
	s_nop 0
	v_add_f32_e32 v7, 1.0, v7
	v_div_scale_f32 v8, s[10:11], v7, v7, v44
	v_rcp_f32_e32 v9, v8
	v_div_scale_f32 v10, vcc, v44, v7, v44
	v_fma_f32 v11, -v8, v9, 1.0
	v_fmac_f32_e32 v9, v11, v9
	v_mul_f32_e32 v11, v10, v9
	v_fma_f32 v12, -v8, v11, v10
	v_fmac_f32_e32 v11, v12, v9
	v_fma_f32 v8, -v8, v11, v10
	v_div_fmas_f32 v8, v8, v9, v11
	v_div_fixup_f32 v2, v8, v7, v44
	ds_write_b32 v6, v2 offset:57344
	s_waitcnt vmcnt(4)
	v_mul_f32_e32 v7, 0xbfb8aa3b, v45
	v_exp_f32_e32 v7, v7
	s_nop 0
	v_add_f32_e32 v7, 1.0, v7
	v_div_scale_f32 v8, s[10:11], v7, v7, v45
	v_rcp_f32_e32 v9, v8
	v_div_scale_f32 v10, vcc, v45, v7, v45
	v_fma_f32 v11, -v8, v9, 1.0
	v_fmac_f32_e32 v9, v11, v9
	v_mul_f32_e32 v11, v10, v9
	v_fma_f32 v12, -v8, v11, v10
	v_fmac_f32_e32 v11, v12, v9
	v_fma_f32 v8, -v8, v11, v10
	v_div_fmas_f32 v8, v8, v9, v11
	v_div_fixup_f32 v2, v8, v7, v45
	ds_write_b32 v6, v2 offset:59392
	s_waitcnt vmcnt(3)
	v_mul_f32_e32 v7, 0xbfb8aa3b, v46
	v_exp_f32_e32 v7, v7
	s_nop 0
	v_add_f32_e32 v7, 1.0, v7
	v_div_scale_f32 v8, s[10:11], v7, v7, v46
	v_rcp_f32_e32 v9, v8
	v_div_scale_f32 v10, vcc, v46, v7, v46
	v_fma_f32 v11, -v8, v9, 1.0
	v_fmac_f32_e32 v9, v11, v9
	v_mul_f32_e32 v11, v10, v9
	v_fma_f32 v12, -v8, v11, v10
	v_fmac_f32_e32 v11, v12, v9
	v_fma_f32 v8, -v8, v11, v10
	v_div_fmas_f32 v8, v8, v9, v11
	v_div_fixup_f32 v2, v8, v7, v46
	ds_write_b32 v6, v2 offset:61440
	s_waitcnt vmcnt(2)
	v_mul_f32_e32 v7, 0xbfb8aa3b, v47
	v_exp_f32_e32 v7, v7
	s_nop 0
	v_add_f32_e32 v7, 1.0, v7
	v_div_scale_f32 v8, s[10:11], v7, v7, v47
	v_rcp_f32_e32 v9, v8
	v_div_scale_f32 v10, vcc, v47, v7, v47
	v_fma_f32 v11, -v8, v9, 1.0
	v_fmac_f32_e32 v9, v11, v9
	v_mul_f32_e32 v11, v10, v9
	v_fma_f32 v12, -v8, v11, v10
	v_fmac_f32_e32 v11, v12, v9
	v_fma_f32 v8, -v8, v11, v10
	v_div_fmas_f32 v8, v8, v9, v11
	v_div_fixup_f32 v2, v8, v7, v47
	ds_write_b32 v6, v2 offset:63488
	v_add_u32_e32 v6, 0x10000, v6
	s_waitcnt vmcnt(1)
	v_mul_f32_e32 v7, 0xbfb8aa3b, v48
	v_exp_f32_e32 v7, v7
	s_nop 0
	v_add_f32_e32 v7, 1.0, v7
	v_div_scale_f32 v8, s[10:11], v7, v7, v48
	v_rcp_f32_e32 v9, v8
	v_div_scale_f32 v10, vcc, v48, v7, v48
	v_fma_f32 v11, -v8, v9, 1.0
	v_fmac_f32_e32 v9, v11, v9
	v_mul_f32_e32 v11, v10, v9
	v_fma_f32 v12, -v8, v11, v10
	v_fmac_f32_e32 v11, v12, v9
	v_fma_f32 v8, -v8, v11, v10
	v_div_fmas_f32 v8, v8, v9, v11
	v_div_fixup_f32 v2, v8, v7, v48
	ds_write_b32 v6, v2 offset:0
	s_waitcnt vmcnt(0)
	v_mul_f32_e32 v7, 0xbfb8aa3b, v49
	v_exp_f32_e32 v7, v7
	s_nop 0
	v_add_f32_e32 v7, 1.0, v7
	v_div_scale_f32 v8, s[10:11], v7, v7, v49
	v_rcp_f32_e32 v9, v8
	v_div_scale_f32 v10, vcc, v49, v7, v49
	v_fma_f32 v11, -v8, v9, 1.0
	v_fmac_f32_e32 v9, v11, v9
	v_mul_f32_e32 v11, v10, v9
	v_fma_f32 v12, -v8, v11, v10
	v_fmac_f32_e32 v11, v12, v9
	v_fma_f32 v8, -v8, v11, v10
	v_div_fmas_f32 v8, v8, v9, v11
	v_div_fixup_f32 v2, v8, v7, v49
	ds_write_b32 v6, v2 offset:2048
	v_sub_u32_e32 v1, 0x87f, v193
	v_lshrrev_b32_e32 v2, 9, v1
	v_add_u32_e32 v1, 2, v2
	s_mov_b32 s6, 0
	v_add_u32_e32 v158, 0, v0
	v_and_b32_e32 v3, 14, v1
	v_mov_b32_e32 v1, v2
	s_mov_b32 s7, 1
	v_add_u32_e32 v4, 0x11800, v158
	s_mov_b64 s[8:9], 0
	v_mov_b32_e32 v5, 0
	s_mov_b32 s10, s6
	s_branch .LBB0_23
